# out-proj GEMM: warm the residual tile into cache with 4 dummy loads per wave before the K-loop
# baseline (speedup 1.0000x reference)
; template <class Epi>
; __device__ __forceinline__ void gemm_phase(LAS unsigned char* lds, const Gemm g, const StaticOrder& S, const Epi& E) {
;     ...
;         const bool has_next = S.next(ui + 1, nxt);
;         const char* nA = has_next ? (const char*)g.A + (size_t)nxt.pm * tstepA + (size_t)(nxt.pn >> 2) * gstepA : cA; const char* nB = has_next ? (const char*)g.Bt + (size_t)nxt.pn * tstepB : cB;
;     ...
; #pragma unroll
;         for (int a = 0; a < 2; ++a)
; #pragma unroll
;             for (int b = 0; b < 2; ++b)
; #pragma unroll
;                 for (int m = 0; m < 4; ++m)
; #pragma unroll
;                     for (int n = 0; n < 2; ++n) acc[a][b][m][n] = (f32x4){0.f, 0.f, 0.f, 0.f};
;         cur = nxt; cA = nA; cB = nB; ++ui;
.LBB0_358:
	v_mov_b64_e32 v[2:3], 0x100
	s_ashr_i32 s17, s16, 31
	v_cmp_lt_i64_e32 vcc, s[18:19], v[2:3]
	s_lshl_b64 s[18:19], s[16:17], 21
	s_add_u32 s18, s38, s18
	s_addc_u32 s19, s39, s19
	s_and_b64 s[20:21], vcc, exec
	s_cselect_b32 s17, s19, s23
	s_cselect_b32 s60, s18, s22
	s_ashr_i32 s15, s14, 31
	s_lshl_b64 s[20:21], s[14:15], 21
	s_add_u32 s20, s46, s20
	s_addc_u32 s21, s47, s21
	s_and_b64 s[24:25], vcc, exec
	s_cselect_b32 s15, s21, s27
	s_cselect_b32 s61, s20, s26
	s_add_u32 s62, s26, 0x100
	v_mov_b32_e32 v2, 0
	s_addc_u32 s63, s27, 0
	s_mov_b32 s64, -2
	v_mov_b32_e32 v3, v2
	v_mov_b32_e32 v4, v2
	v_mov_b32_e32 v5, v2
	v_mov_b32_e32 v6, v2
	v_mov_b32_e32 v7, v2
	v_mov_b32_e32 v8, v2
	v_mov_b32_e32 v9, v2
	v_mov_b32_e32 v18, v2
	v_mov_b32_e32 v19, v2
	v_mov_b32_e32 v20, v2
	v_mov_b32_e32 v21, v2
	v_mov_b32_e32 v22, v2
	v_mov_b32_e32 v23, v2
	v_mov_b32_e32 v24, v2
	v_mov_b32_e32 v25, v2
	v_mov_b32_e32 v34, v2
	v_mov_b32_e32 v35, v2
	v_mov_b32_e32 v36, v2
	v_mov_b32_e32 v37, v2
	v_mov_b32_e32 v38, v2
	v_mov_b32_e32 v39, v2
	v_mov_b32_e32 v40, v2
	v_mov_b32_e32 v41, v2
	v_mov_b32_e32 v50, v2
	v_mov_b32_e32 v51, v2
	v_mov_b32_e32 v52, v2
	v_mov_b32_e32 v53, v2
	v_mov_b32_e32 v54, v2
	v_mov_b32_e32 v55, v2
	v_mov_b32_e32 v56, v2
	v_mov_b32_e32 v57, v2
	v_mov_b32_e32 v10, v2
	v_mov_b32_e32 v11, v2
	v_mov_b32_e32 v12, v2
	v_mov_b32_e32 v13, v2
	v_mov_b32_e32 v14, v2
	v_mov_b32_e32 v15, v2
	v_mov_b32_e32 v16, v2
	v_mov_b32_e32 v17, v2
	v_mov_b32_e32 v26, v2
	v_mov_b32_e32 v27, v2
	v_mov_b32_e32 v28, v2
	v_mov_b32_e32 v29, v2
	v_mov_b32_e32 v30, v2
	v_mov_b32_e32 v31, v2
	v_mov_b32_e32 v32, v2
	v_mov_b32_e32 v33, v2
	v_mov_b32_e32 v42, v2
	v_mov_b32_e32 v43, v2
	v_mov_b32_e32 v44, v2
	v_mov_b32_e32 v45, v2
	v_mov_b32_e32 v46, v2
	v_mov_b32_e32 v47, v2
	v_mov_b32_e32 v48, v2
	v_mov_b32_e32 v49, v2
	v_mov_b32_e32 v58, v2
	v_mov_b32_e32 v59, v2
	v_mov_b32_e32 v60, v2
	v_mov_b32_e32 v61, v2
	v_mov_b32_e32 v62, v2
	v_mov_b32_e32 v63, v2
	v_mov_b32_e32 v64, v2
	v_mov_b32_e32 v65, v2
	v_mov_b32_e32 v66, v2
	v_mov_b32_e32 v67, v2
	v_mov_b32_e32 v68, v2
	v_mov_b32_e32 v69, v2
	v_mov_b32_e32 v78, v2
	v_mov_b32_e32 v79, v2
	v_mov_b32_e32 v80, v2
	v_mov_b32_e32 v81, v2
	v_mov_b32_e32 v98, v2
	v_mov_b32_e32 v99, v2
	v_mov_b32_e32 v100, v2
	v_mov_b32_e32 v101, v2
	v_mov_b32_e32 v102, v2
	v_mov_b32_e32 v103, v2
	v_mov_b32_e32 v104, v2
	v_mov_b32_e32 v105, v2
	v_mov_b32_e32 v114, v2
	v_mov_b32_e32 v115, v2
	v_mov_b32_e32 v116, v2
	v_mov_b32_e32 v117, v2
	v_mov_b32_e32 v118, v2
	v_mov_b32_e32 v119, v2
	v_mov_b32_e32 v120, v2
	v_mov_b32_e32 v121, v2
	v_mov_b32_e32 v130, v2
	v_mov_b32_e32 v131, v2
	v_mov_b32_e32 v132, v2
	v_mov_b32_e32 v133, v2
	v_mov_b32_e32 v134, v2
	v_mov_b32_e32 v135, v2
	v_mov_b32_e32 v136, v2
	v_mov_b32_e32 v137, v2
	v_mov_b32_e32 v90, v2
	v_mov_b32_e32 v91, v2
	v_mov_b32_e32 v92, v2
	v_mov_b32_e32 v93, v2
	v_mov_b32_e32 v94, v2
	v_mov_b32_e32 v95, v2
	v_mov_b32_e32 v96, v2
	v_mov_b32_e32 v97, v2
	v_mov_b32_e32 v106, v2
	v_mov_b32_e32 v107, v2
	v_mov_b32_e32 v108, v2
	v_mov_b32_e32 v109, v2
	v_mov_b32_e32 v110, v2
	v_mov_b32_e32 v111, v2
	v_mov_b32_e32 v112, v2
	v_mov_b32_e32 v113, v2
	v_mov_b32_e32 v122, v2
	v_mov_b32_e32 v123, v2
	v_mov_b32_e32 v124, v2
	v_mov_b32_e32 v125, v2
	v_mov_b32_e32 v126, v2
	v_mov_b32_e32 v127, v2
	v_mov_b32_e32 v128, v2
	v_mov_b32_e32 v129, v2
	v_mov_b32_e32 v138, v2
	v_mov_b32_e32 v139, v2
	v_mov_b32_e32 v140, v2
	v_mov_b32_e32 v141, v2
	v_mov_b32_e32 v142, v2
	v_mov_b32_e32 v143, v2
	v_mov_b32_e32 v144, v2
	v_mov_b32_e32 v145, v2
	s_lshl_b32 s100, s44, 21
	s_lshl_b32 s101, s45, 10
	s_add_i32 s100, s100, s101
	s_add_u32 s100, s0, s100
	s_addc_u32 s101, s1, 0
	v_lshrrev_b32_e32 v222, 3, v232
	v_and_b32_e32 v223, 7, v232
	v_lshlrev_b32_e32 v222, 13, v222
	v_lshl_or_b32 v222, v223, 7, v222
	global_load_dword v224, v222, s[100:101]
	s_add_u32 s100, s100, 0x80000
	s_addc_u32 s101, s101, 0
	global_load_dword v225, v222, s[100:101]
	s_add_u32 s100, s100, 0x80000
	s_addc_u32 s101, s101, 0
	global_load_dword v226, v222, s[100:101]
	s_add_u32 s100, s100, 0x80000
	s_addc_u32 s101, s101, 0
	global_load_dword v227, v222, s[100:101]
